# indexer K stream prefetched two chunks ahead (16 tile loads in flight per wave, loop unrolled by two with a second slot set)
# baseline (speedup 1.0000x reference)
; #define TILE_LOAD(SLOT, CC, TT) do { const bf16_t* kp = P.KI + (rowb + 64 * (CC) + 16 * (TT) + r16) * 64 + 8 * g; Bk[SLOT][0] = *(const bf16x8*)kp; Bk[SLOT][1] = *(const bf16x8*)(kp + 32); } while (0)
; #define TILE_MATH(SLOT, TT) do { _Pragma("unroll") for (int q = 0; q < 4; ++q) { f32x4 a = {0.f, 0.f, 0.f, 0.f}; \
;             a = mfma16(Aq[q][0], Bk[SLOT][0], a); a = mfma16(Aq[q][1], Bk[SLOT][1], a); \
;             pv[q][TT] = wq[q][0] * fmaxf(a[0], 0.f) + wq[q][1] * fmaxf(a[1], 0.f) + wq[q][2] * fmaxf(a[2], 0.f) + wq[q][3] * fmaxf(a[3], 0.f); } } while (0)
; __device__ __forceinline__ void attn_item(const Ptrs& P, unsigned char* lds, int b, int tq0, int tid) {
;     ...
;         for (int q = 0; q < 4; ++q) { const bf16_t* qp = P.QI + (rowb + tq0 + q) * 1024 + r16 * 64 + 8 * g; Aq[q][0] = *(const bf16x8*)qp; Aq[q][1] = *(const bf16x8*)(qp + 32);
;             wq[q] = *(const f32x4*)(P.WI + (rowb + tq0 + q) * 16 + 4 * g); }
;         unsigned* KB = (unsigned*)lds;
;         const int nch = (tmax >> 6) + 1;
;         const int ni = (w < nch) ? ((nch - w + 7) >> 3) : 0;
;         bf16x8 Bk[4][2];
;     ...
;         if (ni > 0) { TILE_LOAD(0, w, 0); TILE_LOAD(1, w, 1); }
; #pragma unroll 1
;         for (int it = 0; it < ni; ++it) {
;             const int c = 8 * it + w; const bool more = it + 1 < ni;
;             float pv[4][4], sv[4];
;             TILE_LOAD(2, c, 2); TILE_MATH(0, 0);
;             TILE_LOAD(3, c, 3); TILE_MATH(1, 1);
;             if (more) TILE_LOAD(0, c + 8, 0);
;             TILE_MATH(2, 2);
;             if (more) TILE_LOAD(1, c + 8, 1);
;             TILE_MATH(3, 3);
.Lq_have_item:
	s_movk_i32 s12, 0x800
	s_waitcnt lgkmcnt(0)
	v_cmp_gt_i32_e32 vcc, s12, v0
	s_mov_b64 s[12:13], -1
	s_and_saveexec_b64 s[70:71], vcc
	s_cbranch_execz .LBB0_465
	v_lshlrev_b32_e32 v64, 2, v0
	v_sub_u32_e32 v124, 0x1ffc, v64
	v_readfirstlane_b32 s63, v188
	s_movk_i32 s12, 0xfc
	s_lshr_b32 s62, s63, 6
	v_cmp_lt_u32_e32 vcc, s12, v124
	s_and_saveexec_b64 s[12:13], vcc
	s_xor_b64 s[60:61], exec, s[12:13]
	s_cbranch_execz .LBB0_913
	v_sub_u32_e32 v126, 0x1fff, v64
	v_lshrrev_b32_e32 v125, 6, v126
	v_subrev_u32_e32 v0, s62, v125
	v_add_u32_e32 v65, 8, v0
	v_cmp_le_u32_e32 vcc, s62, v125
	v_cmp_lt_u32_e64 s[12:13], 7, v65
	s_and_b64 s[14:15], vcc, s[12:13]
	s_and_saveexec_b64 s[12:13], s[14:15]
	s_cbranch_execz .LBB0_479
	s_and_b32 s14, s63, 0xffffffc0
	v_add_u32_e32 v164, s81, v124
	s_ashr_i32 s15, s14, 31
	v_or_b32_e32 v40, 1, v164
	v_mov_b32_e32 v41, v165
	v_or_b32_e32 v32, 2, v164
	v_mov_b32_e32 v33, v165
	v_or_b32_e32 v34, 3, v164
	v_mov_b32_e32 v35, v165
	v_lshl_add_u64 v[48:49], s[14:15], 0, v[182:183]
	v_lshlrev_b64 v[0:1], 11, v[164:165]
	v_lshlrev_b64 v[8:9], 11, v[40:41]
	v_lshlrev_b64 v[16:17], 11, v[32:33]
	v_lshlrev_b64 v[24:25], 11, v[34:35]
	v_lshlrev_b64 v[34:35], 6, v[34:35]
	v_lshlrev_b64 v[32:33], 6, v[32:33]
	v_lshlrev_b64 v[40:41], 6, v[40:41]
	v_lshlrev_b64 v[42:43], 6, v[164:165]
	v_lshlrev_b64 v[48:49], 7, v[48:49]
	v_lshl_add_u64 v[4:5], v[168:169], 0, v[0:1]
	v_lshl_add_u64 v[12:13], v[168:169], 0, v[8:9]
	v_lshl_add_u64 v[20:21], v[168:169], 0, v[16:17]
	v_lshl_add_u64 v[28:29], v[168:169], 0, v[24:25]
	v_lshl_add_u64 v[34:35], v[170:171], 0, v[34:35]
	v_lshl_add_u64 v[36:37], v[170:171], 0, v[32:33]
	v_lshl_add_u64 v[40:41], v[170:171], 0, v[40:41]
	v_lshl_add_u64 v[44:45], v[170:171], 0, v[42:43]
	v_lshl_add_u64 v[60:61], v[172:173], 0, v[48:49]
	global_load_dwordx4 v[0:3], v[4:5], off
	s_nop 0
	global_load_dwordx4 v[4:7], v[4:5], off offset:64
	s_nop 0
	global_load_dwordx4 v[8:11], v[12:13], off
	s_nop 0
	global_load_dwordx4 v[12:15], v[12:13], off offset:64
	s_nop 0
	global_load_dwordx4 v[16:19], v[20:21], off
	s_nop 0
	global_load_dwordx4 v[20:23], v[20:21], off offset:64
	s_nop 0
	global_load_dwordx4 v[24:27], v[28:29], off
	s_nop 0
	global_load_dwordx4 v[28:31], v[28:29], off offset:64
	s_nop 0
	global_load_dwordx4 v[32:35], v[34:35], off
	s_nop 0
	global_load_dwordx4 v[36:39], v[36:37], off
	s_nop 0
	global_load_dwordx4 v[40:43], v[40:41], off
	s_nop 0
	global_load_dwordx4 v[44:47], v[44:45], off
	s_nop 0
	v_lshrrev_b32_e32 v127, 3, v65
	v_sub_u32_e32 v128, 0x1ffd, v64
	v_sub_u32_e32 v129, 0x1ffe, v64
	v_mov_b64_e32 v[150:151], v[60:61]
	s_mov_b64 s[18:19], 0x1000
	v_lshl_add_u64 v[152:153], v[60:61], 0, s[18:19]
	global_load_dwordx4 v[48:51], v[150:151], off
	global_load_dwordx4 v[52:55], v[150:151], off offset:1024
	global_load_dwordx4 v[56:59], v[150:151], off offset:2048
	global_load_dwordx4 v[60:63], v[150:151], off offset:3072
	global_load_dwordx4 v[64:67], v[152:153], off
	global_load_dwordx4 v[68:71], v[152:153], off offset:1024
	global_load_dwordx4 v[72:75], v[152:153], off offset:2048
	global_load_dwordx4 v[76:79], v[152:153], off offset:3072
	s_mov_b64 s[18:19], 0x10000
	v_lshl_add_u64 v[150:151], v[150:151], 0, s[18:19]
	v_lshl_add_u64 v[152:153], v[152:153], 0, s[18:19]
	global_load_dwordx4 v[218:221], v[150:151], off
	global_load_dwordx4 v[222:225], v[150:151], off offset:1024
	global_load_dwordx4 v[226:229], v[150:151], off offset:2048
	global_load_dwordx4 v[230:233], v[150:151], off offset:3072
	global_load_dwordx4 v[234:237], v[152:153], off
	global_load_dwordx4 v[238:241], v[152:153], off offset:1024
	global_load_dwordx4 v[246:249], v[152:153], off offset:2048
	global_load_dwordx4 v[158:161], v[152:153], off offset:3072
	v_lshl_add_u64 v[150:151], v[150:151], 0, s[18:19]
	v_lshl_add_u64 v[152:153], v[152:153], 0, s[18:19]
	s_mov_b32 s20, 0
	v_lshl_add_u32 v130, s62, 8, v203
	v_add_u32_e32 v155, 0x10000, v130
	v_add_u32_e32 v154, s14, v179
	s_nop 0
	v_readfirstlane_b32 s14, v127
.Lidx_loop:
	s_waitcnt vmcnt(14)
	v_mfma_f32_16x16x32_bf16 v[80:83], v[0:3], v[48:51], 0
	v_mfma_f32_16x16x32_bf16 v[84:87], v[8:11], v[48:51], 0
	v_mfma_f32_16x16x32_bf16 v[88:91], v[16:19], v[48:51], 0
	v_mfma_f32_16x16x32_bf16 v[92:95], v[24:27], v[48:51], 0
	v_mfma_f32_16x16x32_bf16 v[80:83], v[4:7], v[52:55], v[80:83]
	v_mfma_f32_16x16x32_bf16 v[84:87], v[12:15], v[52:55], v[84:87]
	v_mfma_f32_16x16x32_bf16 v[88:91], v[20:23], v[52:55], v[88:91]
	v_mfma_f32_16x16x32_bf16 v[92:95], v[28:31], v[52:55], v[92:95]
	global_load_dwordx4 v[48:51], v[150:151], off
	global_load_dwordx4 v[52:55], v[150:151], off offset:1024
	s_waitcnt vmcnt(14)
	v_mfma_f32_16x16x32_bf16 v[96:99], v[0:3], v[56:59], 0
	v_mfma_f32_16x16x32_bf16 v[100:103], v[8:11], v[56:59], 0
	v_mfma_f32_16x16x32_bf16 v[104:107], v[16:19], v[56:59], 0
	v_mfma_f32_16x16x32_bf16 v[108:111], v[24:27], v[56:59], 0
	v_mfma_f32_16x16x32_bf16 v[96:99], v[4:7], v[60:63], v[96:99]
	v_mfma_f32_16x16x32_bf16 v[100:103], v[12:15], v[60:63], v[100:103]
	v_mfma_f32_16x16x32_bf16 v[104:107], v[20:23], v[60:63], v[104:107]
	v_mfma_f32_16x16x32_bf16 v[108:111], v[28:31], v[60:63], v[108:111]
	global_load_dwordx4 v[56:59], v[150:151], off offset:2048
	global_load_dwordx4 v[60:63], v[150:151], off offset:3072
	v_max_f32_e32 v80, 0, v80
	v_max_f32_e32 v84, 0, v84
	v_max_f32_e32 v88, 0, v88
	v_max_f32_e32 v92, 0, v92
	v_max_f32_e32 v81, 0, v81
	v_max_f32_e32 v85, 0, v85
	v_max_f32_e32 v89, 0, v89
	v_max_f32_e32 v93, 0, v93
	v_max_f32_e32 v82, 0, v82
	v_max_f32_e32 v86, 0, v86
	v_max_f32_e32 v90, 0, v90
	v_max_f32_e32 v94, 0, v94
	v_max_f32_e32 v83, 0, v83
	v_max_f32_e32 v87, 0, v87
	v_max_f32_e32 v91, 0, v91
	v_max_f32_e32 v95, 0, v95
	v_mul_f32_e32 v132, v44, v80
	v_mul_f32_e32 v136, v40, v84
	v_mul_f32_e32 v140, v36, v88
	v_mul_f32_e32 v144, v32, v92
	v_fmac_f32_e32 v132, v45, v81
	v_fmac_f32_e32 v136, v41, v85
	v_fmac_f32_e32 v140, v37, v89
	v_fmac_f32_e32 v144, v33, v93
	v_fmac_f32_e32 v132, v46, v82
	v_fmac_f32_e32 v136, v42, v86
	v_fmac_f32_e32 v140, v38, v90
	v_fmac_f32_e32 v144, v34, v94
	v_fmac_f32_e32 v132, v47, v83
	v_fmac_f32_e32 v136, v43, v87
	v_fmac_f32_e32 v140, v39, v91
	v_fmac_f32_e32 v144, v35, v95
	s_waitcnt vmcnt(14)
; __device__ __forceinline__ unsigned f2key(float f) { const unsigned u = __builtin_bit_cast(unsigned, f); return (u & 0x80000000u) ? ~u : (u | 0x80000000u); }
; #define TILE_LOAD(SLOT, CC, TT) do { const bf16_t* kp = P.KI + (rowb + 64 * (CC) + 16 * (TT) + r16) * 64 + 8 * g; Bk[SLOT][0] = *(const bf16x8*)kp; Bk[SLOT][1] = *(const bf16x8*)(kp + 32); } while (0)
; #define TILE_MATH(SLOT, TT) do { _Pragma("unroll") for (int q = 0; q < 4; ++q) { f32x4 a = {0.f, 0.f, 0.f, 0.f}; \
;             a = mfma16(Aq[q][0], Bk[SLOT][0], a); a = mfma16(Aq[q][1], Bk[SLOT][1], a); \
;             pv[q][TT] = wq[q][0] * fmaxf(a[0], 0.f) + wq[q][1] * fmaxf(a[1], 0.f) + wq[q][2] * fmaxf(a[2], 0.f) + wq[q][3] * fmaxf(a[3], 0.f); } } while (0)
; __device__ __forceinline__ void attn_item(const Ptrs& P, unsigned char* lds, int b, int tq0, int tid) {
;     ...
;             TILE_LOAD(2, c, 2); TILE_MATH(0, 0);
;             TILE_LOAD(3, c, 3); TILE_MATH(1, 1);
;             if (more) TILE_LOAD(0, c + 8, 0);
;             TILE_MATH(2, 2);
;             if (more) TILE_LOAD(1, c + 8, 1);
;             TILE_MATH(3, 3);
; #pragma unroll
;             for (int q = 0; q < 4; ++q) { float a0 = pv[q][0], b0 = pv[q][2], a1 = pv[q][1], b1 = pv[q][3];
;                 asm("s_nop 1\n\tv_permlane32_swap_b32 %0, %1" : "+v"(a0), "+v"(b0));
;                 asm("s_nop 1\n\tv_permlane32_swap_b32 %0, %1" : "+v"(a1), "+v"(b1));
;                 float x = a0 + b0, y = a1 + b1;
;                 asm("s_nop 1\n\tv_permlane16_swap_b32 %0, %1" : "+v"(x), "+v"(y));
;                 sv[q] = x + y; }
;             const int s = 64 * c + lane;
; #pragma unroll
;             for (int q = 0; q < 4; ++q) KB[q * 8192 + s] = (s <= tq0 + q) ? f2key(sv[q]) : 0u;
	v_mfma_f32_16x16x32_bf16 v[80:83], v[0:3], v[64:67], 0
	v_mfma_f32_16x16x32_bf16 v[84:87], v[8:11], v[64:67], 0
	v_mfma_f32_16x16x32_bf16 v[88:91], v[16:19], v[64:67], 0
	v_mfma_f32_16x16x32_bf16 v[92:95], v[24:27], v[64:67], 0
	v_mfma_f32_16x16x32_bf16 v[80:83], v[4:7], v[68:71], v[80:83]
	v_mfma_f32_16x16x32_bf16 v[84:87], v[12:15], v[68:71], v[84:87]
	v_mfma_f32_16x16x32_bf16 v[88:91], v[20:23], v[68:71], v[88:91]
	v_mfma_f32_16x16x32_bf16 v[92:95], v[28:31], v[68:71], v[92:95]
	global_load_dwordx4 v[64:67], v[152:153], off
	global_load_dwordx4 v[68:71], v[152:153], off offset:1024
	v_max_f32_e32 v96, 0, v96
	v_max_f32_e32 v100, 0, v100
	v_max_f32_e32 v104, 0, v104
	v_max_f32_e32 v108, 0, v108
	v_max_f32_e32 v97, 0, v97
	v_max_f32_e32 v101, 0, v101
	v_max_f32_e32 v105, 0, v105
	v_max_f32_e32 v109, 0, v109
	v_max_f32_e32 v98, 0, v98
	v_max_f32_e32 v102, 0, v102
	v_max_f32_e32 v106, 0, v106
	v_max_f32_e32 v110, 0, v110
	v_max_f32_e32 v99, 0, v99
	v_max_f32_e32 v103, 0, v103
	v_max_f32_e32 v107, 0, v107
	v_max_f32_e32 v111, 0, v111
	v_mul_f32_e32 v133, v44, v96
	v_mul_f32_e32 v137, v40, v100
	v_mul_f32_e32 v141, v36, v104
	v_mul_f32_e32 v145, v32, v108
	v_fmac_f32_e32 v133, v45, v97
	v_fmac_f32_e32 v137, v41, v101
	v_fmac_f32_e32 v141, v37, v105
	v_fmac_f32_e32 v145, v33, v109
	v_fmac_f32_e32 v133, v46, v98
	v_fmac_f32_e32 v137, v42, v102
	v_fmac_f32_e32 v141, v38, v106
	v_fmac_f32_e32 v145, v34, v110
	v_fmac_f32_e32 v133, v47, v99
	v_fmac_f32_e32 v137, v43, v103
	v_fmac_f32_e32 v141, v39, v107
	v_fmac_f32_e32 v145, v35, v111
	s_waitcnt vmcnt(14)
	v_mfma_f32_16x16x32_bf16 v[96:99], v[0:3], v[72:75], 0
	v_mfma_f32_16x16x32_bf16 v[100:103], v[8:11], v[72:75], 0
	v_mfma_f32_16x16x32_bf16 v[104:107], v[16:19], v[72:75], 0
	v_mfma_f32_16x16x32_bf16 v[108:111], v[24:27], v[72:75], 0
	v_mfma_f32_16x16x32_bf16 v[96:99], v[4:7], v[76:79], v[96:99]
	v_mfma_f32_16x16x32_bf16 v[100:103], v[12:15], v[76:79], v[100:103]
	v_mfma_f32_16x16x32_bf16 v[104:107], v[20:23], v[76:79], v[104:107]
	v_mfma_f32_16x16x32_bf16 v[108:111], v[28:31], v[76:79], v[108:111]
	global_load_dwordx4 v[72:75], v[152:153], off offset:2048
	global_load_dwordx4 v[76:79], v[152:153], off offset:3072
	v_lshl_add_u64 v[150:151], v[150:151], 0, s[18:19]
	v_lshl_add_u64 v[152:153], v[152:153], 0, s[18:19]
	v_max_f32_e32 v80, 0, v80
	v_max_f32_e32 v84, 0, v84
	v_max_f32_e32 v88, 0, v88
	v_max_f32_e32 v92, 0, v92
	v_max_f32_e32 v81, 0, v81
	v_max_f32_e32 v85, 0, v85
	v_max_f32_e32 v89, 0, v89
	v_max_f32_e32 v93, 0, v93
	v_max_f32_e32 v82, 0, v82
	v_max_f32_e32 v86, 0, v86
	v_max_f32_e32 v90, 0, v90
	v_max_f32_e32 v94, 0, v94
	v_max_f32_e32 v83, 0, v83
	v_max_f32_e32 v87, 0, v87
	v_max_f32_e32 v91, 0, v91
	v_max_f32_e32 v95, 0, v95
	v_mul_f32_e32 v134, v44, v80
	v_mul_f32_e32 v138, v40, v84
	v_mul_f32_e32 v142, v36, v88
	v_mul_f32_e32 v146, v32, v92
	v_fmac_f32_e32 v134, v45, v81
	v_fmac_f32_e32 v138, v41, v85
	v_fmac_f32_e32 v142, v37, v89
	v_fmac_f32_e32 v146, v33, v93
	v_fmac_f32_e32 v134, v46, v82
	v_fmac_f32_e32 v138, v42, v86
	v_fmac_f32_e32 v142, v38, v90
	v_fmac_f32_e32 v146, v34, v94
	v_fmac_f32_e32 v134, v47, v83
	v_fmac_f32_e32 v138, v43, v87
	v_fmac_f32_e32 v142, v39, v91
	v_fmac_f32_e32 v146, v35, v95
	v_max_f32_e32 v96, 0, v96
	v_max_f32_e32 v100, 0, v100
	v_max_f32_e32 v104, 0, v104
	v_max_f32_e32 v108, 0, v108
	v_max_f32_e32 v97, 0, v97
	v_max_f32_e32 v101, 0, v101
	v_max_f32_e32 v105, 0, v105
	v_max_f32_e32 v109, 0, v109
	v_max_f32_e32 v98, 0, v98
	v_max_f32_e32 v102, 0, v102
	v_max_f32_e32 v106, 0, v106
	v_max_f32_e32 v110, 0, v110
	v_max_f32_e32 v99, 0, v99
	v_max_f32_e32 v103, 0, v103
	v_max_f32_e32 v107, 0, v107
	v_max_f32_e32 v111, 0, v111
	v_mul_f32_e32 v135, v44, v96
	v_mul_f32_e32 v139, v40, v100
	v_mul_f32_e32 v143, v36, v104
	v_mul_f32_e32 v147, v32, v108
	v_fmac_f32_e32 v135, v45, v97
	v_fmac_f32_e32 v139, v41, v101
	v_fmac_f32_e32 v143, v37, v105
	v_fmac_f32_e32 v147, v33, v109
	v_fmac_f32_e32 v135, v46, v98
	v_fmac_f32_e32 v139, v42, v102
	v_fmac_f32_e32 v143, v38, v106
	v_fmac_f32_e32 v147, v34, v110
	v_fmac_f32_e32 v135, v47, v99
	v_fmac_f32_e32 v139, v43, v103
	v_fmac_f32_e32 v143, v39, v107
	v_fmac_f32_e32 v147, v35, v111
	s_nop 1
	v_permlane32_swap_b32_e32 v132, v134
	v_permlane32_swap_b32_e32 v133, v135
	v_permlane32_swap_b32_e32 v136, v138
	v_permlane32_swap_b32_e32 v137, v139
	v_permlane32_swap_b32_e32 v140, v142
	v_permlane32_swap_b32_e32 v141, v143
	v_permlane32_swap_b32_e32 v144, v146
	v_permlane32_swap_b32_e32 v145, v147
	v_add_f32_e32 v112, v132, v134
	v_add_f32_e32 v113, v133, v135
	v_add_f32_e32 v114, v136, v138
	v_add_f32_e32 v115, v137, v139
	v_add_f32_e32 v116, v140, v142
	v_add_f32_e32 v117, v141, v143
	v_add_f32_e32 v118, v144, v146
	v_add_f32_e32 v119, v145, v147
	s_nop 1
	v_permlane16_swap_b32_e32 v112, v113
	v_permlane16_swap_b32_e32 v114, v115
	v_permlane16_swap_b32_e32 v116, v117
	v_permlane16_swap_b32_e32 v118, v119
	v_add_u32_e32 v156, 0x800, v130
	v_add_u32_e32 v157, 0x800, v155
	v_add_f32_e32 v120, v112, v113
	v_add_f32_e32 v121, v114, v115
	v_add_f32_e32 v122, v116, v117
	v_add_f32_e32 v123, v118, v119
	v_ashrrev_i32_e32 v112, 31, v120
	v_ashrrev_i32_e32 v113, 31, v121
	v_ashrrev_i32_e32 v114, 31, v122
	v_ashrrev_i32_e32 v115, 31, v123
	v_cmp_le_u32_e32 vcc, v154, v124
	v_cmp_le_u32_e64 s[16:17], v154, v128
	v_cmp_le_u32_e64 s[44:45], v154, v129
	v_cmp_le_u32_e64 s[78:79], v154, v126
	v_or_b32_e32 v112, 0x80000000, v112
	v_or_b32_e32 v113, 0x80000000, v113
	v_or_b32_e32 v114, 0x80000000, v114
	v_or_b32_e32 v115, 0x80000000, v115
	v_xor_b32_e32 v120, v120, v112
	v_xor_b32_e32 v121, v121, v113
	v_xor_b32_e32 v122, v122, v114
	v_xor_b32_e32 v123, v123, v115
	v_cndmask_b32_e32 v120, 0, v120, vcc
	v_cndmask_b32_e64 v121, 0, v121, s[16:17]
	v_cndmask_b32_e64 v122, 0, v122, s[44:45]
	v_cndmask_b32_e64 v123, 0, v123, s[78:79]
	ds_write2st64_b32 v130, v120, v121 offset1:128
	ds_write2st64_b32 v155, v122, v123 offset1:128
	v_mov_b32_e32 v130, v156
	v_mov_b32_e32 v155, v157
	v_add_u32_e32 v154, 0x200, v154
	s_add_i32 s20, s20, 1
	s_cmp_lt_u32 s20, s14
	s_cbranch_scc0 .Lidx_exit
; #define TILE_LOAD(SLOT, CC, TT) do { const bf16_t* kp = P.KI + (rowb + 64 * (CC) + 16 * (TT) + r16) * 64 + 8 * g; Bk[SLOT][0] = *(const bf16x8*)kp; Bk[SLOT][1] = *(const bf16x8*)(kp + 32); } while (0)
; #define TILE_MATH(SLOT, TT) do { _Pragma("unroll") for (int q = 0; q < 4; ++q) { f32x4 a = {0.f, 0.f, 0.f, 0.f}; \
;             a = mfma16(Aq[q][0], Bk[SLOT][0], a); a = mfma16(Aq[q][1], Bk[SLOT][1], a); \
;             pv[q][TT] = wq[q][0] * fmaxf(a[0], 0.f) + wq[q][1] * fmaxf(a[1], 0.f) + wq[q][2] * fmaxf(a[2], 0.f) + wq[q][3] * fmaxf(a[3], 0.f); } } while (0)
; __device__ __forceinline__ void attn_item(const Ptrs& P, unsigned char* lds, int b, int tq0, int tid) {
;     ...
;         if (ni > 0) { TILE_LOAD(0, w, 0); TILE_LOAD(1, w, 1); }
; #pragma unroll 1
;         for (int it = 0; it < ni; ++it) {
;             const int c = 8 * it + w; const bool more = it + 1 < ni;
;             float pv[4][4], sv[4];
;             TILE_LOAD(2, c, 2); TILE_MATH(0, 0);
;             TILE_LOAD(3, c, 3); TILE_MATH(1, 1);
;             if (more) TILE_LOAD(0, c + 8, 0);
;             TILE_MATH(2, 2);
;             if (more) TILE_LOAD(1, c + 8, 1);
;             TILE_MATH(3, 3);
	s_waitcnt vmcnt(14)
	v_mfma_f32_16x16x32_bf16 v[80:83], v[0:3], v[218:221], 0
	v_mfma_f32_16x16x32_bf16 v[84:87], v[8:11], v[218:221], 0
	v_mfma_f32_16x16x32_bf16 v[88:91], v[16:19], v[218:221], 0
	v_mfma_f32_16x16x32_bf16 v[92:95], v[24:27], v[218:221], 0
	v_mfma_f32_16x16x32_bf16 v[80:83], v[4:7], v[222:225], v[80:83]
	v_mfma_f32_16x16x32_bf16 v[84:87], v[12:15], v[222:225], v[84:87]
	v_mfma_f32_16x16x32_bf16 v[88:91], v[20:23], v[222:225], v[88:91]
	v_mfma_f32_16x16x32_bf16 v[92:95], v[28:31], v[222:225], v[92:95]
	global_load_dwordx4 v[218:221], v[150:151], off
	global_load_dwordx4 v[222:225], v[150:151], off offset:1024
	s_waitcnt vmcnt(14)
	v_mfma_f32_16x16x32_bf16 v[96:99], v[0:3], v[226:229], 0
	v_mfma_f32_16x16x32_bf16 v[100:103], v[8:11], v[226:229], 0
	v_mfma_f32_16x16x32_bf16 v[104:107], v[16:19], v[226:229], 0
	v_mfma_f32_16x16x32_bf16 v[108:111], v[24:27], v[226:229], 0
	v_mfma_f32_16x16x32_bf16 v[96:99], v[4:7], v[230:233], v[96:99]
	v_mfma_f32_16x16x32_bf16 v[100:103], v[12:15], v[230:233], v[100:103]
	v_mfma_f32_16x16x32_bf16 v[104:107], v[20:23], v[230:233], v[104:107]
	v_mfma_f32_16x16x32_bf16 v[108:111], v[28:31], v[230:233], v[108:111]
	global_load_dwordx4 v[226:229], v[150:151], off offset:2048
	global_load_dwordx4 v[230:233], v[150:151], off offset:3072
	v_max_f32_e32 v80, 0, v80
	v_max_f32_e32 v84, 0, v84
	v_max_f32_e32 v88, 0, v88
	v_max_f32_e32 v92, 0, v92
	v_max_f32_e32 v81, 0, v81
	v_max_f32_e32 v85, 0, v85
	v_max_f32_e32 v89, 0, v89
	v_max_f32_e32 v93, 0, v93
	v_max_f32_e32 v82, 0, v82
	v_max_f32_e32 v86, 0, v86
	v_max_f32_e32 v90, 0, v90
	v_max_f32_e32 v94, 0, v94
	v_max_f32_e32 v83, 0, v83
	v_max_f32_e32 v87, 0, v87
	v_max_f32_e32 v91, 0, v91
	v_max_f32_e32 v95, 0, v95
	v_mul_f32_e32 v132, v44, v80
	v_mul_f32_e32 v136, v40, v84
	v_mul_f32_e32 v140, v36, v88
	v_mul_f32_e32 v144, v32, v92
	v_fmac_f32_e32 v132, v45, v81
	v_fmac_f32_e32 v136, v41, v85
	v_fmac_f32_e32 v140, v37, v89
	v_fmac_f32_e32 v144, v33, v93
	v_fmac_f32_e32 v132, v46, v82
	v_fmac_f32_e32 v136, v42, v86
	v_fmac_f32_e32 v140, v38, v90
	v_fmac_f32_e32 v144, v34, v94
	v_fmac_f32_e32 v132, v47, v83
	v_fmac_f32_e32 v136, v43, v87
	v_fmac_f32_e32 v140, v39, v91
	v_fmac_f32_e32 v144, v35, v95
	s_waitcnt vmcnt(14)
	v_mfma_f32_16x16x32_bf16 v[80:83], v[0:3], v[234:237], 0
	v_mfma_f32_16x16x32_bf16 v[84:87], v[8:11], v[234:237], 0
	v_mfma_f32_16x16x32_bf16 v[88:91], v[16:19], v[234:237], 0
	v_mfma_f32_16x16x32_bf16 v[92:95], v[24:27], v[234:237], 0
	v_mfma_f32_16x16x32_bf16 v[80:83], v[4:7], v[238:241], v[80:83]
	v_mfma_f32_16x16x32_bf16 v[84:87], v[12:15], v[238:241], v[84:87]
	v_mfma_f32_16x16x32_bf16 v[88:91], v[20:23], v[238:241], v[88:91]
	v_mfma_f32_16x16x32_bf16 v[92:95], v[28:31], v[238:241], v[92:95]
	global_load_dwordx4 v[234:237], v[152:153], off
	global_load_dwordx4 v[238:241], v[152:153], off offset:1024
	v_max_f32_e32 v96, 0, v96
	v_max_f32_e32 v100, 0, v100
	v_max_f32_e32 v104, 0, v104
	v_max_f32_e32 v108, 0, v108
	v_max_f32_e32 v97, 0, v97
	v_max_f32_e32 v101, 0, v101
	v_max_f32_e32 v105, 0, v105
	v_max_f32_e32 v109, 0, v109
	v_max_f32_e32 v98, 0, v98
	v_max_f32_e32 v102, 0, v102
	v_max_f32_e32 v106, 0, v106
	v_max_f32_e32 v110, 0, v110
	v_max_f32_e32 v99, 0, v99
	v_max_f32_e32 v103, 0, v103
	v_max_f32_e32 v107, 0, v107
	v_max_f32_e32 v111, 0, v111
	v_mul_f32_e32 v133, v44, v96
	v_mul_f32_e32 v137, v40, v100
	v_mul_f32_e32 v141, v36, v104
	v_mul_f32_e32 v145, v32, v108
	v_fmac_f32_e32 v133, v45, v97
	v_fmac_f32_e32 v137, v41, v101
	v_fmac_f32_e32 v141, v37, v105
	v_fmac_f32_e32 v145, v33, v109
	v_fmac_f32_e32 v133, v46, v98
	v_fmac_f32_e32 v137, v42, v102
	v_fmac_f32_e32 v141, v38, v106
	v_fmac_f32_e32 v145, v34, v110
	v_fmac_f32_e32 v133, v47, v99
	v_fmac_f32_e32 v137, v43, v103
	v_fmac_f32_e32 v141, v39, v107
	v_fmac_f32_e32 v145, v35, v111
	s_waitcnt vmcnt(14)
; __device__ __forceinline__ unsigned f2key(float f) { const unsigned u = __builtin_bit_cast(unsigned, f); return (u & 0x80000000u) ? ~u : (u | 0x80000000u); }
; #define TILE_LOAD(SLOT, CC, TT) do { const bf16_t* kp = P.KI + (rowb + 64 * (CC) + 16 * (TT) + r16) * 64 + 8 * g; Bk[SLOT][0] = *(const bf16x8*)kp; Bk[SLOT][1] = *(const bf16x8*)(kp + 32); } while (0)
; #define TILE_MATH(SLOT, TT) do { _Pragma("unroll") for (int q = 0; q < 4; ++q) { f32x4 a = {0.f, 0.f, 0.f, 0.f}; \
;             a = mfma16(Aq[q][0], Bk[SLOT][0], a); a = mfma16(Aq[q][1], Bk[SLOT][1], a); \
;             pv[q][TT] = wq[q][0] * fmaxf(a[0], 0.f) + wq[q][1] * fmaxf(a[1], 0.f) + wq[q][2] * fmaxf(a[2], 0.f) + wq[q][3] * fmaxf(a[3], 0.f); } } while (0)
; __device__ __forceinline__ void attn_item(const Ptrs& P, unsigned char* lds, int b, int tq0, int tid) {
;     ...
;             TILE_MATH(2, 2);
;             if (more) TILE_LOAD(1, c + 8, 1);
;             TILE_MATH(3, 3);
; #pragma unroll
;             for (int q = 0; q < 4; ++q) { float a0 = pv[q][0], b0 = pv[q][2], a1 = pv[q][1], b1 = pv[q][3];
;                 asm("s_nop 1\n\tv_permlane32_swap_b32 %0, %1" : "+v"(a0), "+v"(b0));
;                 asm("s_nop 1\n\tv_permlane32_swap_b32 %0, %1" : "+v"(a1), "+v"(b1));
;                 float x = a0 + b0, y = a1 + b1;
;                 asm("s_nop 1\n\tv_permlane16_swap_b32 %0, %1" : "+v"(x), "+v"(y));
;                 sv[q] = x + y; }
;             const int s = 64 * c + lane;
; #pragma unroll
;             for (int q = 0; q < 4; ++q) KB[q * 8192 + s] = (s <= tq0 + q) ? f2key(sv[q]) : 0u;
	v_mfma_f32_16x16x32_bf16 v[96:99], v[0:3], v[246:249], 0
	v_mfma_f32_16x16x32_bf16 v[100:103], v[8:11], v[246:249], 0
	v_mfma_f32_16x16x32_bf16 v[104:107], v[16:19], v[246:249], 0
	v_mfma_f32_16x16x32_bf16 v[108:111], v[24:27], v[246:249], 0
	v_mfma_f32_16x16x32_bf16 v[96:99], v[4:7], v[158:161], v[96:99]
	v_mfma_f32_16x16x32_bf16 v[100:103], v[12:15], v[158:161], v[100:103]
	v_mfma_f32_16x16x32_bf16 v[104:107], v[20:23], v[158:161], v[104:107]
	v_mfma_f32_16x16x32_bf16 v[108:111], v[28:31], v[158:161], v[108:111]
	global_load_dwordx4 v[246:249], v[152:153], off offset:2048
	global_load_dwordx4 v[158:161], v[152:153], off offset:3072
	v_lshl_add_u64 v[150:151], v[150:151], 0, s[18:19]
	v_lshl_add_u64 v[152:153], v[152:153], 0, s[18:19]
	v_max_f32_e32 v80, 0, v80
	v_max_f32_e32 v84, 0, v84
	v_max_f32_e32 v88, 0, v88
	v_max_f32_e32 v92, 0, v92
	v_max_f32_e32 v81, 0, v81
	v_max_f32_e32 v85, 0, v85
	v_max_f32_e32 v89, 0, v89
	v_max_f32_e32 v93, 0, v93
	v_max_f32_e32 v82, 0, v82
	v_max_f32_e32 v86, 0, v86
	v_max_f32_e32 v90, 0, v90
	v_max_f32_e32 v94, 0, v94
	v_max_f32_e32 v83, 0, v83
	v_max_f32_e32 v87, 0, v87
	v_max_f32_e32 v91, 0, v91
	v_max_f32_e32 v95, 0, v95
	v_mul_f32_e32 v134, v44, v80
	v_mul_f32_e32 v138, v40, v84
	v_mul_f32_e32 v142, v36, v88
	v_mul_f32_e32 v146, v32, v92
	v_fmac_f32_e32 v134, v45, v81
	v_fmac_f32_e32 v138, v41, v85
	v_fmac_f32_e32 v142, v37, v89
	v_fmac_f32_e32 v146, v33, v93
	v_fmac_f32_e32 v134, v46, v82
	v_fmac_f32_e32 v138, v42, v86
	v_fmac_f32_e32 v142, v38, v90
	v_fmac_f32_e32 v146, v34, v94
	v_fmac_f32_e32 v134, v47, v83
	v_fmac_f32_e32 v138, v43, v87
	v_fmac_f32_e32 v142, v39, v91
	v_fmac_f32_e32 v146, v35, v95
	v_max_f32_e32 v96, 0, v96
	v_max_f32_e32 v100, 0, v100
	v_max_f32_e32 v104, 0, v104
	v_max_f32_e32 v108, 0, v108
	v_max_f32_e32 v97, 0, v97
	v_max_f32_e32 v101, 0, v101
	v_max_f32_e32 v105, 0, v105
	v_max_f32_e32 v109, 0, v109
	v_max_f32_e32 v98, 0, v98
	v_max_f32_e32 v102, 0, v102
	v_max_f32_e32 v106, 0, v106
	v_max_f32_e32 v110, 0, v110
	v_max_f32_e32 v99, 0, v99
	v_max_f32_e32 v103, 0, v103
	v_max_f32_e32 v107, 0, v107
	v_max_f32_e32 v111, 0, v111
	v_mul_f32_e32 v135, v44, v96
	v_mul_f32_e32 v139, v40, v100
	v_mul_f32_e32 v143, v36, v104
	v_mul_f32_e32 v147, v32, v108
	v_fmac_f32_e32 v135, v45, v97
	v_fmac_f32_e32 v139, v41, v101
	v_fmac_f32_e32 v143, v37, v105
	v_fmac_f32_e32 v147, v33, v109
	v_fmac_f32_e32 v135, v46, v98
	v_fmac_f32_e32 v139, v42, v102
	v_fmac_f32_e32 v143, v38, v106
	v_fmac_f32_e32 v147, v34, v110
	v_fmac_f32_e32 v135, v47, v99
	v_fmac_f32_e32 v139, v43, v103
	v_fmac_f32_e32 v143, v39, v107
	v_fmac_f32_e32 v147, v35, v111
	s_nop 1
	v_permlane32_swap_b32_e32 v132, v134
	v_permlane32_swap_b32_e32 v133, v135
	v_permlane32_swap_b32_e32 v136, v138
	v_permlane32_swap_b32_e32 v137, v139
	v_permlane32_swap_b32_e32 v140, v142
	v_permlane32_swap_b32_e32 v141, v143
	v_permlane32_swap_b32_e32 v144, v146
	v_permlane32_swap_b32_e32 v145, v147
	v_add_f32_e32 v112, v132, v134
	v_add_f32_e32 v113, v133, v135
	v_add_f32_e32 v114, v136, v138
	v_add_f32_e32 v115, v137, v139
	v_add_f32_e32 v116, v140, v142
	v_add_f32_e32 v117, v141, v143
	v_add_f32_e32 v118, v144, v146
	v_add_f32_e32 v119, v145, v147
	s_nop 1
	v_permlane16_swap_b32_e32 v112, v113
	v_permlane16_swap_b32_e32 v114, v115
	v_permlane16_swap_b32_e32 v116, v117
	v_permlane16_swap_b32_e32 v118, v119
	v_add_u32_e32 v156, 0x800, v130
	v_add_u32_e32 v157, 0x800, v155
	v_add_f32_e32 v120, v112, v113
	v_add_f32_e32 v121, v114, v115
	v_add_f32_e32 v122, v116, v117
	v_add_f32_e32 v123, v118, v119
	v_ashrrev_i32_e32 v112, 31, v120
	v_ashrrev_i32_e32 v113, 31, v121
	v_ashrrev_i32_e32 v114, 31, v122
	v_ashrrev_i32_e32 v115, 31, v123
	v_cmp_le_u32_e32 vcc, v154, v124
	v_cmp_le_u32_e64 s[16:17], v154, v128
	v_cmp_le_u32_e64 s[44:45], v154, v129
	v_cmp_le_u32_e64 s[78:79], v154, v126
	v_or_b32_e32 v112, 0x80000000, v112
	v_or_b32_e32 v113, 0x80000000, v113
	v_or_b32_e32 v114, 0x80000000, v114
	v_or_b32_e32 v115, 0x80000000, v115
	v_xor_b32_e32 v120, v120, v112
	v_xor_b32_e32 v121, v121, v113
	v_xor_b32_e32 v122, v122, v114
	v_xor_b32_e32 v123, v123, v115
	v_cndmask_b32_e32 v120, 0, v120, vcc
	v_cndmask_b32_e64 v121, 0, v121, s[16:17]
	v_cndmask_b32_e64 v122, 0, v122, s[44:45]
	v_cndmask_b32_e64 v123, 0, v123, s[78:79]
	ds_write2st64_b32 v130, v120, v121 offset1:128
	ds_write2st64_b32 v155, v122, v123 offset1:128
	v_mov_b32_e32 v130, v156
	v_mov_b32_e32 v155, v157
	v_add_u32_e32 v154, 0x200, v154
	s_add_i32 s20, s20, 1
	s_cmp_lt_u32 s20, s14
	s_cbranch_scc1 .Lidx_loop
.Lidx_exit:
	s_waitcnt vmcnt(0)
	s_branch .LBB0_479
	s_nop 0
	s_nop 0
	s_nop 0
	s_nop 0
